# attention queues LPT-like order with T1=12
# baseline (speedup 1.0000x reference)
; __device__ __forceinline__ int fresh_lane() { int l; asm volatile("v_mbcnt_lo_u32_b32 %0, -1, 0\n\tv_mbcnt_hi_u32_b32 %0, -1, %0" : "=v"(l)); return l; }
; #define SEAM(k) do { if (IN(k) && IN((k) + 1)) xcd_barrier(bar, C.wave); } while (0)
; #define PH5 { phase_attention(P, C, (P.pad >> 8) & 3, P.li); }
; #define RUN(k, BODY) do { if (IN(k)) { unsigned char* ws = P.ws; LAUNDER_GPTR(ws); BODY } } while (0)
; __device__ __forceinline__ void phase_attention(const Params& P, const Ctx& C, int parts, int qset) {
;     ...
;     for (int i = 0; i < 8; ++i) { const int x = (x0 + i) & 7;
;         for (;;) {
;             __syncthreads();
;             if (C.wave == 0 && fresh_lane() == 0) *slot = __hip_atomic_fetch_add(qc + 64 * x, 1u, __ATOMIC_RELAXED, __HIP_MEMORY_SCOPE_AGENT);
;             __syncthreads();
;             const unsigned u = *slot;
;             if (u >= 128u) break;
;             const int us = __builtin_amdgcn_readfirstlane((int)u);
; __global__ void __launch_bounds__(NWAVES * 64, 2) fwd_kernel(Params P) {
;     ...
;     RUN(3, PH3); SEAM(3);
;     RUN(4, PH4);
;     RUN(5, PH5); SEAM(5);
.LBB0_1136:
	s_bitcmp1_b32 s101, 1
	s_cbranch_scc1 .Lmy_e7
	s_bitset1_b32 s101, 1
	s_cmpk_lg_i32 s68, 0x100
	s_cbranch_scc1 .Lmy_e7
	s_bitset1_b32 s101, 3
	v_readlane_b32 s99, v254, 10
	s_cmpk_lt_u32 s99, 192
	s_cbranch_scc1 .Lmy_e7
	s_and_b32 s100, s99, 31
	s_mul_i32 s100, s100, 3
	s_add_i32 s100, s100, 12
	s_bitset1_b32 s101, 0
	s_waitcnt vmcnt(0)
	s_barrier
	s_mov_b64 s[2:3], -1
	s_branch .LBB0_1192

; __device__ __forceinline__ int fresh_lane() { int l; asm volatile("v_mbcnt_lo_u32_b32 %0, -1, 0\n\tv_mbcnt_hi_u32_b32 %0, -1, %0" : "=v"(l)); return l; }
; __device__ __forceinline__ void phase_attention(const Params& P, const Ctx& C, int parts, int qset) {
;     ...
;             __syncthreads();
;             if (C.wave == 0 && fresh_lane() == 0) *slot = __hip_atomic_fetch_add(qc + 64 * x, 1u, __ATOMIC_RELAXED, __HIP_MEMORY_SCOPE_AGENT);
;             __syncthreads();
;             const unsigned u = *slot;
;             if (u >= 128u) break;
;             const int us = __builtin_amdgcn_readfirstlane((int)u);
;             int pq = -1, dq = -1;
;             if (us < 96) { const int k = us / 3, r = us - 3 * k; if (r == 0) pq = 63 - k; else dq = 2 * k + r - 1; } else pq = 127 - us;
.LBB0_1208:
	s_waitcnt lgkmcnt(0)
	s_barrier
	ds_read_b32 v0, v218
	s_movk_i32 s2, 0x7f
	s_waitcnt lgkmcnt(0)
	v_cmp_lt_u32_e32 vcc, s2, v0
	s_mov_b64 s[2:3], -1
	s_cbranch_vccnz .LBB0_1201
	v_readfirstlane_b32 s5, v0
	s_cmpk_gt_i32 s5, 107
	s_cbranch_scc1 .LBB0_1213
	s_andn2_b64 vcc, exec, s[2:3]
	s_mov_b32 s4, -1
	s_cbranch_vccz .LBB0_1214

; __device__ __forceinline__ void phase_attention(const Params& P, const Ctx& C, int parts, int qset) {
;     ...
;             const int us = __builtin_amdgcn_readfirstlane((int)u);
;             int pq = -1, dq = -1;
;             if (us < 96) { const int k = us / 3, r = us - 3 * k; if (r == 0) pq = 63 - k; else dq = 2 * k + r - 1; } else pq = 127 - us;
;             if (pq >= 0) { if (parts & 1) { if (fixed_ok) attn_prompt_unit<true>(P, C, x, pq); else attn_prompt_unit<false>(P, C, x, pq); } }
.LBB0_1214:
	s_sub_i32 s3, s5, 12
	s_mul_hi_i32 s2, s3, 0x55555556
	s_mul_i32 s4, s2, -3
	s_add_i32 s4, s4, s3
	s_lshl_b32 s64, s2, 1
	s_add_i32 s64, s64, s4
	s_sub_i32 s2, 51, s2
	s_cmp_eq_u32 s4, 2
	s_cselect_b32 s2, s2, -1
	s_cselect_b32 s4, -1, s64
	s_sub_i32 s3, 63, s5
	s_cmpk_lt_i32 s5, 12
	s_cselect_b32 s64, s3, s2
	s_cselect_b32 s4, -1, s4
	s_cmp_lt_i32 s64, 0
	s_mov_b64 s[2:3], -1
	s_cbranch_scc0 .LBB0_1212
